# P8 step loop head aligned to 64 bytes
# speedup vs baseline: 1.0093x; 1.0069x over previous
.LBB0_906:
	s_cmp_lt_i32 s90, 9
	s_cselect_b64 s[2:3], -1, 0
	s_and_b64 s[38:39], s[2:3], s[0:1]
	s_andn2_b64 vcc, exec, s[38:39]
	s_cbranch_vccnz .LBB0_998
	s_mov_b64 s[70:71], s[62:63]
	s_mov_b32 s68, s59
	s_mov_b64 s[66:67], s[60:61]
	s_cmpk_gt_i32 s58, 0xff
	v_readfirstlane_b32 s20, v0
	s_cbranch_scc1 .LBB0_997
	v_readlane_b32 s15, v251, 48
	v_readfirstlane_b32 s35, v0
	s_lshr_b32 s35, s35, 6
	s_and_b32 s36, s35, 3
	s_lshr_b32 s37, s35, 2
	s_and_b32 s31, s15, 1
	s_bfe_u32 s73, s15, 0x20001
	s_bfe_u32 s74, s15, 0x20003
	s_lshr_b32 s72, s15, 5
	s_lshl_b32 s33, s72, 8
	s_addk_i32 s33, 0x4000
	s_lshl_b32 s34, s72, 11
	s_addk_i32 s34, 0xff00
	s_movk_i32 s48, 0x1800
	s_movk_i32 s49, 0x400
	s_cmp_eq_u32 s31, 0
	s_cselect_b32 s30, s48, s49
	s_lshl_b32 s48, s73, 8
	s_add_u32 s49, s88, 0xa27d000
	s_addc_u32 s52, s89, 0
	s_cmp_eq_u32 s31, 0
	s_cselect_b32 s16, s96, s49
	s_cselect_b32 s17, s97, s52
	s_add_u32 s16, s16, s48
	s_addc_u32 s17, s17, 0
	s_add_u32 s49, s88, 0xb27d000
	s_addc_u32 s52, s89, 0
	s_add_u32 s53, s96, 0x400
	s_addc_u32 s64, s97, 0
	s_cmp_eq_u32 s31, 0
	s_cselect_b32 s18, s53, s49
	s_cselect_b32 s19, s64, s52
	s_add_u32 s18, s18, s48
	s_addc_u32 s19, s19, 0
	s_lshl_b32 s49, s73, 9
	s_lshl_b32 s52, s74, 7
	s_add_i32 s49, s49, s52
	s_add_i32 s52, s49, 0x800
	s_add_u32 s20, s96, s52
	s_addc_u32 s21, s97, 0
	v_readlane_b32 s28, v251, 34
	v_readlane_b32 s29, v251, 35
	s_lshl_b32 s52, s31, 25
	s_add_i32 s52, s52, s49
	s_add_u32 s28, s28, s52
	s_addc_u32 s29, s29, 0
	s_lshl_b32 s49, s31, 3
	s_add_i32 s49, s49, s72
	s_lshl_b32 s49, s49, 2
	s_add_i32 s49, s49, s73
	s_mul_i32 s49, s49, 0x4800
	s_add_u32 s22, s88, 0x115d000
	s_addc_u32 s23, s89, 0
	s_add_u32 s22, s22, s49
	s_addc_u32 s23, s23, 0
	v_bfe_u32 v94, v0, 4, 2
	v_lshrrev_b32_e32 v95, 2, v186
	v_and_b32_e32 v96, 3, v186
	v_mov_b32_e32 v97, 272
	v_mul_u32_u24_e32 v98, v186, v97
	v_lshl_add_u32 v182, v94, 4, v98
	v_lshl_add_u32 v183, v94, 3, v98
	v_mov_b32_e32 v97, 288
	v_mul_u32_u24_e32 v98, v186, v97
	v_lshl_add_u32 v242, v94, 4, v98
	v_lshl_add_u32 v99, v94, 2, v95
	v_mul_u32_u24_e32 v185, v99, v97
	v_lshl_add_u32 v185, v96, 3, v185
	v_mov_b32_e32 v97, 160
	v_mul_u32_u24_e32 v184, v99, v97
	v_lshl_add_u32 v184, v96, 3, v184
	s_lshl_b32 s49, s36, 5
	v_add_u32_e32 v184, s49, v184
	v_lshlrev_b32_e32 v188, 4, v94
	v_add_u32_e32 v188, 0x16800, v188
	v_lshrrev_b32_e32 v95, 4, v0
	v_mov_b32_e32 v97, 272
	v_mul_u32_u24_e32 v189, v95, v97
	v_lshl_add_u32 v189, v186, 4, v189
	v_mov_b32_e32 v97, 288
	v_mul_u32_u24_e32 v243, v95, v97
	v_lshl_add_u32 v243, v186, 4, v243
	v_lshrrev_b32_e32 v96, 3, v0
	v_and_b32_e32 v98, 7, v0
	v_mov_b32_e32 v97, 160
	v_mul_u32_u24_e32 v190, v96, v97
	v_lshl_add_u32 v190, v98, 4, v190
	v_add_u32_e32 v191, 0x16800, v194
	s_cmp_gt_u32 s35, 1
	s_cselect_b32 s52, 0x200, 0
	v_add_u32_e32 v191, s52, v191
	s_cmp_eq_u32 s31, 0
	s_cselect_b64 vcc, -1, 0
	v_sub_u32_e32 v99, 63, v95
	v_cndmask_b32_e32 v99, v99, v95, vcc
	v_mul_lo_u32 v244, v99, s30
	v_lshl_add_u32 v244, v186, 4, v244
	v_add_u32_e32 v95, 32, v95
	v_sub_u32_e32 v99, 63, v95
	v_cndmask_b32_e32 v99, v99, v95, vcc
	v_mul_lo_u32 v245, v99, s30
	v_lshl_add_u32 v245, v186, 4, v245
	v_sub_u32_e32 v99, 63, v96
	v_cndmask_b32_e32 v99, v99, v96, vcc
	v_mov_b32_e32 v97, 0x1800
	v_mul_lo_u32 v246, v99, v97
	v_lshl_add_u32 v246, v98, 4, v246
	v_sub_u32_e32 v99, 15, v186
	v_cndmask_b32_e32 v99, v99, v186, vcc
	v_lshlrev_b32_e32 v247, 11, v99
	v_lshl_add_u32 v247, v94, 3, v247
	v_add_u32_e32 v247, s49, v247
	v_lshlrev_b32_e32 v95, 2, v94
	s_lshl_b32 s52, s35, 1
	s_lshr_b32 s75, 0xa90f, s52
	s_and_b32 s75, s75, 3
	s_lshr_b32 s98, 0xa008, s52
	s_and_b32 s98, s98, 3
	s_lshr_b32 s99, 0xa50d, s52
	s_and_b32 s99, s99, 3
	v_cmp_gt_u32_e64 s[92:93], v95, v186
	s_nop 1
	s_cmp_eq_u32 s98, s75
	s_cselect_b64 s[40:41], s[92:93], 0
	s_cmp_eq_u32 s99, s75
	s_cselect_b64 s[80:81], s[92:93], 0
	v_add_u32_e32 v96, 1, v95
	v_cmp_gt_u32_e64 s[92:93], v96, v186
	s_nop 1
	s_cmp_eq_u32 s98, s75
	s_cselect_b64 s[42:43], s[92:93], 0
	s_cmp_eq_u32 s99, s75
	s_cselect_b64 s[82:83], s[92:93], 0
	v_add_u32_e32 v96, 2, v95
	v_cmp_gt_u32_e64 s[92:93], v96, v186
	s_nop 1
	s_cmp_eq_u32 s98, s75
	s_cselect_b64 s[44:45], s[92:93], 0
	s_cmp_eq_u32 s99, s75
	s_cselect_b64 s[84:85], s[92:93], 0
	v_add_u32_e32 v96, 3, v95
	v_cmp_gt_u32_e64 s[92:93], v96, v186
	s_nop 1
	s_cmp_eq_u32 s98, s75
	s_cselect_b64 s[46:47], s[92:93], 0
	s_cmp_eq_u32 s99, s75
	s_cselect_b64 s[86:87], s[92:93], 0
	s_mul_i32 s52, s98, 4608
	v_add_u32_e32 v54, s52, v242
	s_mul_i32 s52, s99, 4608
	v_add_u32_e32 v55, s52, v242
	s_mul_i32 s52, s75, 4352
	v_add_u32_e32 v56, s52, v182
	v_mov_b32_e32 v97, 160
	v_mul_u32_u24_e32 v59, v186, v97
	v_lshl_add_u32 v59, v94, 4, v59
	v_add_u32_e32 v59, 0x17800, v59
	s_mul_i32 s52, s75, 2560
	s_lshr_b32 s53, s98, 1
	s_lshl_b32 s53, s53, 6
	s_add_i32 s53, s53, s52
	s_and_b32 s64, s98, 1
	s_lshl_b32 s64, s64, 3
	s_add_i32 s53, s53, s64
	v_add_u32_e32 v57, s53, v59
	s_lshr_b32 s53, s99, 1
	s_lshl_b32 s53, s53, 6
	s_add_i32 s53, s53, s52
	s_and_b32 s64, s99, 1
	s_lshl_b32 s64, s64, 3
	s_add_i32 s53, s53, s64
	v_add_u32_e32 v58, s53, v59
	v_lshlrev_b32_e32 v96, 4, v0
	v_add_u32_e32 v96, 0x17800, v96
	v_mov_b32_e32 v42, 0
	v_mov_b32_e32 v43, 0
	v_mov_b32_e32 v44, 0
	v_mov_b32_e32 v45, 0
	ds_write_b128 v96, v[42:45]
	ds_write_b128 v96, v[42:45] offset:8192
	v_mov_b32_e32 v2, 0
	v_mov_b32_e32 v3, 0
	v_mov_b32_e32 v4, 0
	v_mov_b32_e32 v5, 0
	v_mov_b32_e32 v6, 0
	v_mov_b32_e32 v7, 0
	v_mov_b32_e32 v8, 0
	v_mov_b32_e32 v9, 0
	v_mov_b32_e32 v10, 0
	v_mov_b32_e32 v11, 0
	v_mov_b32_e32 v12, 0
	v_mov_b32_e32 v13, 0
	v_mov_b32_e32 v14, 0
	v_mov_b32_e32 v15, 0
	v_mov_b32_e32 v16, 0
	v_mov_b32_e32 v17, 0
	v_mov_b32_e32 v18, 0
	v_mov_b32_e32 v19, 0
	v_mov_b32_e32 v20, 0
	v_mov_b32_e32 v21, 0
	v_mov_b32_e32 v22, 0
	v_mov_b32_e32 v23, 0
	v_mov_b32_e32 v24, 0
	v_mov_b32_e32 v25, 0
	v_mov_b32_e32 v26, 0
	v_mov_b32_e32 v27, 0
	v_mov_b32_e32 v28, 0
	v_mov_b32_e32 v29, 0
	v_mov_b32_e32 v30, 0
	v_mov_b32_e32 v31, 0
	v_mov_b32_e32 v32, 0
	v_mov_b32_e32 v33, 0
	v_add_u32_e32 v182, 0xb400, v182
	v_add_u32_e32 v183, 0xb400, v183
	v_add_u32_e32 v184, 0xb400, v184
	v_add_u32_e32 v185, 0xb400, v185
	v_add_u32_e32 v242, 0xb400, v242
	v_add_u32_e32 v54, 0xb400, v54
	v_add_u32_e32 v55, 0xb400, v55
	v_add_u32_e32 v56, 0xb400, v56
	v_add_u32_e32 v188, 0x200, v188
	s_mov_b32 s64, 0
	s_min_u32 s65, s64, 35
	s_sub_i32 s48, 3, s65
	s_sub_i32 s49, 39, s65
	s_cmp_lt_u32 s65, 4
	s_cselect_b32 s48, s48, s49
	s_cmp_eq_u32 s31, 0
	s_cselect_b32 s54, s65, s48
	s_lshl_b32 s48, s54, 6
	s_add_i32 s49, s33, s48
	s_add_i32 s48, s34, s48
	s_cmp_lt_u32 s54, 4
	s_cselect_b32 s55, s49, s48
	s_mul_i32 s48, s55, s30
	s_add_u32 s0, s16, s48
	s_addc_u32 s1, s17, 0
	s_add_u32 s2, s18, s48
	s_addc_u32 s3, s19, 0
	s_mul_i32 s48, s55, 0x1800
	s_add_u32 s4, s20, s48
	s_addc_u32 s5, s21, 0
	s_lshl_b32 s48, s54, 9
	s_add_u32 s6, s22, s48
	s_addc_u32 s7, s23, 0
	global_load_dwordx4 v[224:227], v244, s[2:3]
	global_load_dwordx4 v[228:231], v245, s[2:3]
	global_load_dwordx4 v[232:235], v246, s[4:5]
	global_load_dwordx4 v[216:219], v244, s[0:1]
	global_load_dwordx4 v[220:223], v245, s[0:1]
	global_load_dword v236, v194, s[6:7]
	s_mov_b32 s64, 1
	s_min_u32 s65, s64, 35
	s_sub_i32 s48, 3, s65
	s_sub_i32 s49, 39, s65
	s_cmp_lt_u32 s65, 4
	s_cselect_b32 s48, s48, s49
	s_cmp_eq_u32 s31, 0
	s_cselect_b32 s54, s65, s48
	s_lshl_b32 s48, s54, 6
	s_add_i32 s49, s33, s48
	s_add_i32 s48, s34, s48
	s_cmp_lt_u32 s54, 4
	s_cselect_b32 s55, s49, s48
	s_mul_i32 s48, s55, s30
	s_add_u32 s0, s16, s48
	s_addc_u32 s1, s17, 0
	s_add_u32 s2, s18, s48
	s_addc_u32 s3, s19, 0
	s_mul_i32 s48, s55, 0x1800
	s_add_u32 s4, s20, s48
	s_addc_u32 s5, s21, 0
	s_lshl_b32 s48, s54, 9
	s_add_u32 s6, s22, s48
	s_addc_u32 s7, s23, 0
	global_load_dwordx4 v[142:145], v244, s[2:3]
	global_load_dwordx4 v[146:149], v245, s[2:3]
	global_load_dwordx4 v[238:241], v246, s[4:5]
	global_load_dwordx4 v[134:137], v244, s[0:1]
	global_load_dwordx4 v[138:141], v245, s[0:1]
	global_load_dword v237, v194, s[6:7]
	s_waitcnt vmcnt(6)
	ds_write_b128 v243, v[224:227] offset:17408
	ds_write_b128 v243, v[228:231] offset:26624
	ds_write_b128 v190, v[232:235] offset:35840
	ds_write_b128 v189, v[216:219]
	ds_write_b128 v189, v[220:223] offset:8704
	ds_write_b32 v191, v236
	s_mov_b32 s64, 2
	s_min_u32 s65, s64, 35
	s_sub_i32 s48, 3, s65
	s_sub_i32 s49, 39, s65
	s_cmp_lt_u32 s65, 4
	s_cselect_b32 s48, s48, s49
	s_cmp_eq_u32 s31, 0
	s_cselect_b32 s54, s65, s48
	s_lshl_b32 s48, s54, 6
	s_add_i32 s49, s33, s48
	s_add_i32 s48, s34, s48
	s_cmp_lt_u32 s54, 4
	s_cselect_b32 s55, s49, s48
	s_mul_i32 s48, s55, s30
	s_add_u32 s0, s16, s48
	s_addc_u32 s1, s17, 0
	s_add_u32 s2, s18, s48
	s_addc_u32 s3, s19, 0
	s_mul_i32 s48, s55, 0x1800
	s_add_u32 s4, s20, s48
	s_addc_u32 s5, s21, 0
	s_lshl_b32 s48, s54, 9
	s_add_u32 s6, s22, s48
	s_addc_u32 s7, s23, 0
	global_load_dwordx4 v[224:227], v244, s[2:3]
	global_load_dwordx4 v[228:231], v245, s[2:3]
	global_load_dwordx4 v[232:235], v246, s[4:5]
	global_load_dwordx4 v[216:219], v244, s[0:1]
	global_load_dwordx4 v[220:223], v245, s[0:1]
	global_load_dword v236, v194, s[6:7]
	s_mov_b32 s12, 0
	s_waitcnt lgkmcnt(0)
	s_barrier
	.p2align 6
